# v35 + NSA: remaining lane^32 denominator sums (branch switch, item epilogue) via v_permlane32_swap
# baseline (speedup 1.0000x reference)
; DI unsigned pk2(float lo, float hi) { const f32x2 v = {lo, hi}; const bf16x2_t b = __builtin_convertvector(v, bf16x2_t); return __builtin_bit_cast(unsigned, b); }
; DI void nsa_item(KA a, LAS unsigned char* lds, const int it) {
;     ...
;     { const float lt = l_run + __shfl_xor(l_run, 32); const float sc = g2 / lt; of[0] += ot[0] * sc; of[1] += ot[1] * sc; }
;     ...
; #pragma unroll
;     for (int dh = 0; dh < 2; ++dh)
; #pragma unroll
;         for (int q4 = 0; q4 < 4; ++q4) { v2u p; p.x = pk2(of[dh][4 * q4], of[dh][4 * q4 + 1]); p.y = pk2(of[dh][4 * q4 + 2], of[dh][4 * q4 + 3]);
;             *(v2u*)(act + tokrow * D + 512 + head * 64 + 32 * dh + 8 * q4 + 4 * hf) = p; }
.LBB0_601:
	s_waitcnt vmcnt(3)
	v_lshlrev_b32_e32 v32, 16, v91
	v_mul_f32_e32 v32, 0xbfb8aa3b, v32
	v_exp_f32_e32 v32, v32
	v_mov_b32_e32 v33, v135
	v_mov_b32_e32 v34, v135
	v_mov_b32_e32 v93, v193
	v_add_f32_e32 v32, 1.0, v32
	v_rcp_f32_e32 v32, v32
	s_waitcnt lgkmcnt(0)
	v_permlane32_swap_b32_e32 v33, v34
	v_add_f32_e32 v33, v34, v33
	v_div_scale_f32 v34, s[0:1], v33, v33, v32
	v_rcp_f32_e32 v35, v34
	v_div_scale_f32 v36, vcc, v32, v33, v32
	v_readlane_b32 s0, v254, 44
	v_fma_f32 v37, -v34, v35, 1.0
	v_fmac_f32_e32 v35, v37, v35
	v_mul_f32_e32 v37, v36, v35
	v_fma_f32 v38, -v34, v37, v36
	v_fmac_f32_e32 v37, v38, v35
	v_fma_f32 v34, -v34, v37, v36
	v_div_fmas_f32 v34, v34, v35, v37
	v_div_fixup_f32 v32, v34, v33, v32
	v_pk_fma_f32 v[30:31], v[30:31], v[32:33], v[124:125] op_sel_hi:[1,0,1]
	v_pk_fma_f32 v[28:29], v[28:29], v[32:33], v[120:121] op_sel_hi:[1,0,1]
	v_pk_fma_f32 v[26:27], v[26:27], v[32:33], v[116:117] op_sel_hi:[1,0,1]
	v_pk_fma_f32 v[24:25], v[24:25], v[32:33], v[112:113] op_sel_hi:[1,0,1]
	v_pk_fma_f32 v[22:23], v[22:23], v[32:33], v[108:109] op_sel_hi:[1,0,1]
	v_pk_fma_f32 v[20:21], v[20:21], v[32:33], v[104:105] op_sel_hi:[1,0,1]
	v_pk_fma_f32 v[18:19], v[18:19], v[32:33], v[100:101] op_sel_hi:[1,0,1]
	v_pk_fma_f32 v[16:17], v[16:17], v[32:33], v[96:97] op_sel_hi:[1,0,1]
	v_pk_fma_f32 v[14:15], v[14:15], v[32:33], v[122:123] op_sel_hi:[1,0,1]
	v_pk_fma_f32 v[12:13], v[12:13], v[32:33], v[118:119] op_sel_hi:[1,0,1]
	v_pk_fma_f32 v[10:11], v[10:11], v[32:33], v[114:115] op_sel_hi:[1,0,1]
	v_pk_fma_f32 v[8:9], v[8:9], v[32:33], v[110:111] op_sel_hi:[1,0,1]
	v_pk_fma_f32 v[6:7], v[6:7], v[32:33], v[106:107] op_sel_hi:[1,0,1]
	v_pk_fma_f32 v[4:5], v[4:5], v[32:33], v[102:103] op_sel_hi:[1,0,1]
	v_pk_fma_f32 v[2:3], v[2:3], v[32:33], v[98:99] op_sel_hi:[1,0,1]
	v_pk_fma_f32 v[0:1], v[0:1], v[32:33], v[94:95] op_sel_hi:[1,0,1]
	v_lshlrev_b64 v[32:33], 11, v[86:87]
	v_readlane_b32 s1, v254, 45
	v_cvt_pk_bf16_f32 v16, v16, v17
	v_cvt_pk_bf16_f32 v17, v18, v19
	v_lshl_add_u64 v[32:33], s[0:1], 0, v[32:33]
	v_lshl_add_u64 v[32:33], v[84:85], 1, v[32:33]
	v_lshl_add_u64 v[32:33], v[92:93], 1, v[32:33]
	s_mov_b64 s[0:1], 0x4000400
	v_lshl_add_u64 v[34:35], v[32:33], 0, s[0:1]
	s_brev_b32 s0, 32
	v_add_co_u32_e32 v18, vcc, s0, v32
	v_cvt_pk_bf16_f32 v0, v0, v1
	s_nop 0
	v_addc_co_u32_e32 v19, vcc, 0, v33, vcc
	v_cvt_pk_bf16_f32 v1, v2, v3
	global_store_dwordx2 v[18:19], v[16:17], off offset:1024
	v_cvt_pk_bf16_f32 v16, v20, v21
	v_cvt_pk_bf16_f32 v17, v22, v23
	global_store_dwordx2 v[34:35], v[0:1], off offset:64
	v_cvt_pk_bf16_f32 v0, v4, v5
	v_cvt_pk_bf16_f32 v1, v6, v7
	global_store_dwordx2 v[34:35], v[16:17], off offset:16
	v_cvt_pk_bf16_f32 v16, v24, v25
	v_cvt_pk_bf16_f32 v17, v26, v27
	global_store_dwordx2 v[34:35], v[0:1], off offset:80
	v_cvt_pk_bf16_f32 v0, v8, v9
	v_cvt_pk_bf16_f32 v1, v10, v11
	global_store_dwordx2 v[34:35], v[16:17], off offset:32
	v_cvt_pk_bf16_f32 v16, v28, v29
	v_cvt_pk_bf16_f32 v17, v30, v31
	global_store_dwordx2 v[34:35], v[0:1], off offset:96
	v_cvt_pk_bf16_f32 v0, v12, v13
	v_cvt_pk_bf16_f32 v1, v14, v15
	s_mov_b64 s[0:1], 0
	global_store_dwordx2 v[34:35], v[16:17], off offset:48
	global_store_dwordx2 v[34:35], v[0:1], off offset:112

; #define LAS __attribute__((address_space(3)))
; DI void nsa_item(KA a, LAS unsigned char* lds, const int it) {
;     ...
;         const int desc = LIST[i]; const int ty = desc >> 8, j = desc & 255;
;         const LAS bf16* Kc = (i & 1) ? Kt1 : Kt; const LAS bf16* Vc = (i & 1) ? VT1 : VT;
;         if (ty != curtype) { const float lt = l_run + __shfl_xor(l_run, 32); const float sc = g1 / lt; of[0] += ot[0] * sc; of[1] += ot[1] * sc; ot[0] = ZERO16; ot[1] = ZERO16; m_ref = 0.f; l_run = 0.f; curtype = ty; }
.LBB0_796:
	s_waitcnt lgkmcnt(10)
	v_readfirstlane_b32 s78, v191
	s_ashr_i32 s82, s78, 8
	s_cmp_eq_u32 s82, s88
	s_cbranch_scc1 .LBB0_798
	v_mov_b32_e32 v32, v135
	v_mov_b32_e32 v137, 0
	s_mov_b32 s88, s82
	s_nop 0
	v_permlane32_swap_b32_e32 v32, v135
	v_add_f32_e32 v32, v135, v32
	v_div_scale_f32 v33, s[74:75], v32, v32, v93
	v_rcp_f32_e32 v34, v33
	v_div_scale_f32 v35, vcc, v93, v32, v93
	v_mov_b32_e32 v135, 0
	v_fma_f32 v36, -v33, v34, 1.0
	v_fmac_f32_e32 v34, v36, v34
	v_mul_f32_e32 v36, v35, v34
	v_fma_f32 v37, -v33, v36, v35
	v_fmac_f32_e32 v36, v37, v34
	v_fma_f32 v33, -v33, v36, v35
	v_div_fmas_f32 v33, v33, v34, v36
	v_div_fixup_f32 v32, v33, v32, v93
	v_pk_fma_f32 v[124:125], v[30:31], v[32:33], v[124:125] op_sel_hi:[1,0,1]
	v_pk_fma_f32 v[120:121], v[28:29], v[32:33], v[120:121] op_sel_hi:[1,0,1]
	v_pk_fma_f32 v[116:117], v[26:27], v[32:33], v[116:117] op_sel_hi:[1,0,1]
	v_pk_fma_f32 v[112:113], v[24:25], v[32:33], v[112:113] op_sel_hi:[1,0,1]
	v_pk_fma_f32 v[108:109], v[22:23], v[32:33], v[108:109] op_sel_hi:[1,0,1]
	v_pk_fma_f32 v[104:105], v[20:21], v[32:33], v[104:105] op_sel_hi:[1,0,1]
	v_pk_fma_f32 v[100:101], v[18:19], v[32:33], v[100:101] op_sel_hi:[1,0,1]
	v_pk_fma_f32 v[96:97], v[16:17], v[32:33], v[96:97] op_sel_hi:[1,0,1]
	v_pk_fma_f32 v[122:123], v[14:15], v[32:33], v[122:123] op_sel_hi:[1,0,1]
	v_pk_fma_f32 v[118:119], v[12:13], v[32:33], v[118:119] op_sel_hi:[1,0,1]
	v_pk_fma_f32 v[114:115], v[10:11], v[32:33], v[114:115] op_sel_hi:[1,0,1]
	v_pk_fma_f32 v[110:111], v[8:9], v[32:33], v[110:111] op_sel_hi:[1,0,1]
	v_pk_fma_f32 v[106:107], v[6:7], v[32:33], v[106:107] op_sel_hi:[1,0,1]
	v_pk_fma_f32 v[102:103], v[4:5], v[32:33], v[102:103] op_sel_hi:[1,0,1]
	v_pk_fma_f32 v[98:99], v[2:3], v[32:33], v[98:99] op_sel_hi:[1,0,1]
	v_pk_fma_f32 v[94:95], v[0:1], v[32:33], v[94:95] op_sel_hi:[1,0,1]
	v_mov_b32_e32 v0, 0
	v_mov_b32_e32 v1, v137
	v_mov_b32_e32 v2, v137
	v_mov_b32_e32 v3, v137
	v_mov_b32_e32 v4, v137
	v_mov_b32_e32 v5, v137
	v_mov_b32_e32 v6, v137
	v_mov_b32_e32 v7, v137
	v_mov_b32_e32 v8, v137
	v_mov_b32_e32 v9, v137
	v_mov_b32_e32 v10, v137
	v_mov_b32_e32 v11, v137
	v_mov_b32_e32 v12, v137
	v_mov_b32_e32 v13, v137
	v_mov_b32_e32 v14, v137
	v_mov_b32_e32 v15, v137
	v_mov_b32_e32 v16, 0
	v_mov_b32_e32 v17, v137
	v_mov_b32_e32 v18, v137
	v_mov_b32_e32 v19, v137
	v_mov_b32_e32 v20, v137
	v_mov_b32_e32 v21, v137
	v_mov_b32_e32 v22, v137
	v_mov_b32_e32 v23, v137
	v_mov_b32_e32 v24, v137
	v_mov_b32_e32 v25, v137
	v_mov_b32_e32 v26, v137
	v_mov_b32_e32 v27, v137
	v_mov_b32_e32 v28, v137
	v_mov_b32_e32 v29, v137
	v_mov_b32_e32 v30, v137
	v_mov_b32_e32 v31, v137
